# f18 + GLA chunk-state scan with all 64 steps of loads issued up front (deep prefetch), stores behind sliding vmcnt
# baseline (speedup 1.0000x reference)
; __device__ __forceinline__ unsigned pk2(float lo, float hi) { f32x2 v = {lo, hi}; bf16x2_t b = __builtin_convertvector(v, bf16x2_t); return __builtin_bit_cast(unsigned, b); }
; __device__ __forceinline__ float bflo(unsigned u) { return __uint_as_float(u << 16); }
; __device__ __forceinline__ float bfhi(unsigned u) { return __uint_as_float(u & 0xffff0000u); }
; __device__ __forceinline__ void gla_scan(Frame& F) {
;     const int NT = F.G * 512;
;     for (int e = F.vcu * 512 + F.tid; e < 8 * 256 * 64; e += NT) {
;         const int bh = e >> 14, rem = e & 16383, dv = rem >> 6, dk = (rem & 63) * 2;
;         unsigned* sb = (unsigned*)(WSP(bf16, WS_SB) + (size_t)bh * 64 * 256 * 128 + (size_t)dv * 128 + dk);
;         const float* dec = WSP(float, WS_DEC) + (size_t)bh * 64 * 128 + dk;
;         float s0 = 0.f, s1 = 0.f;
; #pragma unroll 8
;         for (int n = 0; n < 64; ++n) { const unsigned inc = sb[(size_t)n * 256 * 64]; const f32x2 d = *(const f32x2*)(dec + n * 128);
;             sb[(size_t)n * 256 * 64] = pk2(s0, s1); s0 = d.x * s0 + bflo(inc); s1 = d.y * s1 + bfhi(inc); }
;     }
; }
.LBB0_696:
	v_ashrrev_i32_e32 v4, 14, v8
	v_lshlrev_b32_e32 v2, 1, v9
	v_ashrrev_i32_e32 v5, 31, v4
	v_and_b32_e32 v6, 0xff00, v2
	v_and_b32_e32 v7, 0xfc, v2
	v_lshlrev_b64 v[2:3], 22, v[4:5]
	v_lshlrev_b32_e32 v10, 2, v9
	v_lshlrev_b64 v[4:5], 15, v[4:5]
	v_or3_b32 v2, v2, v6, v7
	v_mov_b32_e32 v6, 0
	v_and_or_b32 v4, v10, s13, v4
	s_mov_b32 s18, 64
	v_mov_b32_e32 v7, v6
	s_add_u32 s98, s34, 0x5a00000
	s_addc_u32 s99, s35, 0
	s_add_u32 s100, s34, 0x14a000
	s_addc_u32 s101, s35, 0
	global_load_dword v28, v2, s[98:99]
	s_add_u32 s98, s98, 0x10000
	s_addc_u32 s99, s99, 0
	global_load_dwordx2 v[92:93], v4, s[100:101]
	global_load_dword v29, v2, s[98:99]
	s_add_u32 s98, s98, 0x10000
	s_addc_u32 s99, s99, 0
	global_load_dwordx2 v[94:95], v4, s[100:101] offset:512
	global_load_dword v30, v2, s[98:99]
	s_add_u32 s98, s98, 0x10000
	s_addc_u32 s99, s99, 0
	global_load_dwordx2 v[96:97], v4, s[100:101] offset:1024
	global_load_dword v31, v2, s[98:99]
	s_add_u32 s98, s98, 0x10000
	s_addc_u32 s99, s99, 0
	global_load_dwordx2 v[98:99], v4, s[100:101] offset:1536
	global_load_dword v32, v2, s[98:99]
	s_add_u32 s98, s98, 0x10000
	s_addc_u32 s99, s99, 0
	global_load_dwordx2 v[100:101], v4, s[100:101] offset:2048
	global_load_dword v33, v2, s[98:99]
	s_add_u32 s98, s98, 0x10000
	s_addc_u32 s99, s99, 0
	global_load_dwordx2 v[102:103], v4, s[100:101] offset:2560
	global_load_dword v34, v2, s[98:99]
	s_add_u32 s98, s98, 0x10000
	s_addc_u32 s99, s99, 0
	global_load_dwordx2 v[104:105], v4, s[100:101] offset:3072
	global_load_dword v35, v2, s[98:99]
	s_add_u32 s98, s98, 0x10000
	s_addc_u32 s99, s99, 0
	global_load_dwordx2 v[106:107], v4, s[100:101] offset:3584
	s_add_u32 s100, s100, 0x1000
	s_addc_u32 s101, s101, 0
	global_load_dword v36, v2, s[98:99]
	s_add_u32 s98, s98, 0x10000
	s_addc_u32 s99, s99, 0
	global_load_dwordx2 v[108:109], v4, s[100:101]
	global_load_dword v37, v2, s[98:99]
	s_add_u32 s98, s98, 0x10000
	s_addc_u32 s99, s99, 0
	global_load_dwordx2 v[110:111], v4, s[100:101] offset:512
	global_load_dword v38, v2, s[98:99]
	s_add_u32 s98, s98, 0x10000
	s_addc_u32 s99, s99, 0
	global_load_dwordx2 v[112:113], v4, s[100:101] offset:1024
	global_load_dword v39, v2, s[98:99]
	s_add_u32 s98, s98, 0x10000
	s_addc_u32 s99, s99, 0
	global_load_dwordx2 v[114:115], v4, s[100:101] offset:1536
	global_load_dword v40, v2, s[98:99]
	s_add_u32 s98, s98, 0x10000
	s_addc_u32 s99, s99, 0
	global_load_dwordx2 v[116:117], v4, s[100:101] offset:2048
	global_load_dword v41, v2, s[98:99]
	s_add_u32 s98, s98, 0x10000
	s_addc_u32 s99, s99, 0
	global_load_dwordx2 v[118:119], v4, s[100:101] offset:2560
	global_load_dword v42, v2, s[98:99]
	s_add_u32 s98, s98, 0x10000
	s_addc_u32 s99, s99, 0
	global_load_dwordx2 v[120:121], v4, s[100:101] offset:3072
	global_load_dword v43, v2, s[98:99]
	s_add_u32 s98, s98, 0x10000
	s_addc_u32 s99, s99, 0
	global_load_dwordx2 v[122:123], v4, s[100:101] offset:3584
	s_add_u32 s100, s100, 0x1000
	s_addc_u32 s101, s101, 0
	global_load_dword v44, v2, s[98:99]
	s_add_u32 s98, s98, 0x10000
	s_addc_u32 s99, s99, 0
	global_load_dwordx2 v[124:125], v4, s[100:101]
	global_load_dword v45, v2, s[98:99]
	s_add_u32 s98, s98, 0x10000
	s_addc_u32 s99, s99, 0
	global_load_dwordx2 v[126:127], v4, s[100:101] offset:512
	global_load_dword v46, v2, s[98:99]
	s_add_u32 s98, s98, 0x10000
	s_addc_u32 s99, s99, 0
	global_load_dwordx2 v[128:129], v4, s[100:101] offset:1024
	global_load_dword v47, v2, s[98:99]
	s_add_u32 s98, s98, 0x10000
	s_addc_u32 s99, s99, 0
	global_load_dwordx2 v[130:131], v4, s[100:101] offset:1536
	global_load_dword v48, v2, s[98:99]
	s_add_u32 s98, s98, 0x10000
	s_addc_u32 s99, s99, 0
	global_load_dwordx2 v[132:133], v4, s[100:101] offset:2048
	global_load_dword v49, v2, s[98:99]
	s_add_u32 s98, s98, 0x10000
	s_addc_u32 s99, s99, 0
	global_load_dwordx2 v[134:135], v4, s[100:101] offset:2560
	global_load_dword v50, v2, s[98:99]
	s_add_u32 s98, s98, 0x10000
	s_addc_u32 s99, s99, 0
	global_load_dwordx2 v[136:137], v4, s[100:101] offset:3072
	global_load_dword v51, v2, s[98:99]
	s_add_u32 s98, s98, 0x10000
	s_addc_u32 s99, s99, 0
	global_load_dwordx2 v[138:139], v4, s[100:101] offset:3584
	s_add_u32 s100, s100, 0x1000
	s_addc_u32 s101, s101, 0
	global_load_dword v52, v2, s[98:99]
	s_add_u32 s98, s98, 0x10000
	s_addc_u32 s99, s99, 0
	global_load_dwordx2 v[140:141], v4, s[100:101]
	global_load_dword v53, v2, s[98:99]
	s_add_u32 s98, s98, 0x10000
	s_addc_u32 s99, s99, 0
	global_load_dwordx2 v[142:143], v4, s[100:101] offset:512
	global_load_dword v54, v2, s[98:99]
	s_add_u32 s98, s98, 0x10000
	s_addc_u32 s99, s99, 0
	global_load_dwordx2 v[144:145], v4, s[100:101] offset:1024
	global_load_dword v55, v2, s[98:99]
	s_add_u32 s98, s98, 0x10000
	s_addc_u32 s99, s99, 0
	global_load_dwordx2 v[146:147], v4, s[100:101] offset:1536
	global_load_dword v56, v2, s[98:99]
	s_add_u32 s98, s98, 0x10000
	s_addc_u32 s99, s99, 0
	global_load_dwordx2 v[148:149], v4, s[100:101] offset:2048
	global_load_dword v57, v2, s[98:99]
	s_add_u32 s98, s98, 0x10000
	s_addc_u32 s99, s99, 0
	global_load_dwordx2 v[150:151], v4, s[100:101] offset:2560
	global_load_dword v58, v2, s[98:99]
	s_add_u32 s98, s98, 0x10000
	s_addc_u32 s99, s99, 0
	global_load_dwordx2 v[152:153], v4, s[100:101] offset:3072
	global_load_dword v59, v2, s[98:99]
	s_add_u32 s98, s98, 0x10000
	s_addc_u32 s99, s99, 0
	global_load_dwordx2 v[154:155], v4, s[100:101] offset:3584
	s_add_u32 s100, s100, 0x1000
	s_addc_u32 s101, s101, 0
	global_load_dword v60, v2, s[98:99]
	s_add_u32 s98, s98, 0x10000
	s_addc_u32 s99, s99, 0
	global_load_dwordx2 v[156:157], v4, s[100:101]
	global_load_dword v61, v2, s[98:99]
	s_add_u32 s98, s98, 0x10000
; __device__ __forceinline__ unsigned pk2(float lo, float hi) { f32x2 v = {lo, hi}; bf16x2_t b = __builtin_convertvector(v, bf16x2_t); return __builtin_bit_cast(unsigned, b); }
; __device__ __forceinline__ float bflo(unsigned u) { return __uint_as_float(u << 16); }
; __device__ __forceinline__ float bfhi(unsigned u) { return __uint_as_float(u & 0xffff0000u); }
; __device__ __forceinline__ void gla_scan(Frame& F) {
;     const int NT = F.G * 512;
;     for (int e = F.vcu * 512 + F.tid; e < 8 * 256 * 64; e += NT) {
;         const int bh = e >> 14, rem = e & 16383, dv = rem >> 6, dk = (rem & 63) * 2;
;         unsigned* sb = (unsigned*)(WSP(bf16, WS_SB) + (size_t)bh * 64 * 256 * 128 + (size_t)dv * 128 + dk);
;         const float* dec = WSP(float, WS_DEC) + (size_t)bh * 64 * 128 + dk;
;         float s0 = 0.f, s1 = 0.f;
; #pragma unroll 8
;         for (int n = 0; n < 64; ++n) { const unsigned inc = sb[(size_t)n * 256 * 64]; const f32x2 d = *(const f32x2*)(dec + n * 128);
;             sb[(size_t)n * 256 * 64] = pk2(s0, s1); s0 = d.x * s0 + bflo(inc); s1 = d.y * s1 + bfhi(inc); }
;     }
; }
	s_addc_u32 s99, s99, 0
	global_load_dwordx2 v[158:159], v4, s[100:101] offset:512
	global_load_dword v62, v2, s[98:99]
	s_add_u32 s98, s98, 0x10000
	s_addc_u32 s99, s99, 0
	global_load_dwordx2 v[160:161], v4, s[100:101] offset:1024
	global_load_dword v63, v2, s[98:99]
	s_add_u32 s98, s98, 0x10000
	s_addc_u32 s99, s99, 0
	global_load_dwordx2 v[162:163], v4, s[100:101] offset:1536
	global_load_dword v64, v2, s[98:99]
	s_add_u32 s98, s98, 0x10000
	s_addc_u32 s99, s99, 0
	global_load_dwordx2 v[164:165], v4, s[100:101] offset:2048
	global_load_dword v65, v2, s[98:99]
	s_add_u32 s98, s98, 0x10000
	s_addc_u32 s99, s99, 0
	global_load_dwordx2 v[166:167], v4, s[100:101] offset:2560
	global_load_dword v66, v2, s[98:99]
	s_add_u32 s98, s98, 0x10000
	s_addc_u32 s99, s99, 0
	global_load_dwordx2 v[168:169], v4, s[100:101] offset:3072
	global_load_dword v67, v2, s[98:99]
	s_add_u32 s98, s98, 0x10000
	s_addc_u32 s99, s99, 0
	global_load_dwordx2 v[170:171], v4, s[100:101] offset:3584
	s_add_u32 s100, s100, 0x1000
	s_addc_u32 s101, s101, 0
	global_load_dword v68, v2, s[98:99]
	s_add_u32 s98, s98, 0x10000
	s_addc_u32 s99, s99, 0
	global_load_dwordx2 v[172:173], v4, s[100:101]
	global_load_dword v69, v2, s[98:99]
	s_add_u32 s98, s98, 0x10000
	s_addc_u32 s99, s99, 0
	global_load_dwordx2 v[174:175], v4, s[100:101] offset:512
	global_load_dword v70, v2, s[98:99]
	s_add_u32 s98, s98, 0x10000
	s_addc_u32 s99, s99, 0
	global_load_dwordx2 v[176:177], v4, s[100:101] offset:1024
	global_load_dword v71, v2, s[98:99]
	s_add_u32 s98, s98, 0x10000
	s_addc_u32 s99, s99, 0
	global_load_dwordx2 v[178:179], v4, s[100:101] offset:1536
	global_load_dword v72, v2, s[98:99]
	s_add_u32 s98, s98, 0x10000
	s_addc_u32 s99, s99, 0
	global_load_dwordx2 v[180:181], v4, s[100:101] offset:2048
	global_load_dword v73, v2, s[98:99]
	s_add_u32 s98, s98, 0x10000
	s_addc_u32 s99, s99, 0
	global_load_dwordx2 v[182:183], v4, s[100:101] offset:2560
	global_load_dword v74, v2, s[98:99]
	s_add_u32 s98, s98, 0x10000
	s_addc_u32 s99, s99, 0
	global_load_dwordx2 v[184:185], v4, s[100:101] offset:3072
	global_load_dword v75, v2, s[98:99]
	s_add_u32 s98, s98, 0x10000
	s_addc_u32 s99, s99, 0
	global_load_dwordx2 v[186:187], v4, s[100:101] offset:3584
	s_add_u32 s100, s100, 0x1000
	s_addc_u32 s101, s101, 0
	global_load_dword v76, v2, s[98:99]
	s_add_u32 s98, s98, 0x10000
	s_addc_u32 s99, s99, 0
	global_load_dwordx2 v[188:189], v4, s[100:101]
	global_load_dword v77, v2, s[98:99]
	s_add_u32 s98, s98, 0x10000
	s_addc_u32 s99, s99, 0
	global_load_dwordx2 v[190:191], v4, s[100:101] offset:512
	global_load_dword v78, v2, s[98:99]
	s_add_u32 s98, s98, 0x10000
	s_addc_u32 s99, s99, 0
	global_load_dwordx2 v[192:193], v4, s[100:101] offset:1024
	global_load_dword v79, v2, s[98:99]
	s_add_u32 s98, s98, 0x10000
	s_addc_u32 s99, s99, 0
	global_load_dwordx2 v[194:195], v4, s[100:101] offset:1536
	global_load_dword v80, v2, s[98:99]
	s_add_u32 s98, s98, 0x10000
	s_addc_u32 s99, s99, 0
	global_load_dwordx2 v[196:197], v4, s[100:101] offset:2048
	global_load_dword v81, v2, s[98:99]
	s_add_u32 s98, s98, 0x10000
	s_addc_u32 s99, s99, 0
	global_load_dwordx2 v[198:199], v4, s[100:101] offset:2560
	global_load_dword v82, v2, s[98:99]
	s_add_u32 s98, s98, 0x10000
	s_addc_u32 s99, s99, 0
	global_load_dwordx2 v[200:201], v4, s[100:101] offset:3072
	global_load_dword v83, v2, s[98:99]
	s_add_u32 s98, s98, 0x10000
	s_addc_u32 s99, s99, 0
	global_load_dwordx2 v[202:203], v4, s[100:101] offset:3584
	s_add_u32 s100, s100, 0x1000
	s_addc_u32 s101, s101, 0
	global_load_dword v84, v2, s[98:99]
	s_add_u32 s98, s98, 0x10000
	s_addc_u32 s99, s99, 0
	global_load_dwordx2 v[204:205], v4, s[100:101]
	global_load_dword v85, v2, s[98:99]
	s_add_u32 s98, s98, 0x10000
	s_addc_u32 s99, s99, 0
	global_load_dwordx2 v[206:207], v4, s[100:101] offset:512
	global_load_dword v86, v2, s[98:99]
	s_add_u32 s98, s98, 0x10000
	s_addc_u32 s99, s99, 0
	global_load_dwordx2 v[208:209], v4, s[100:101] offset:1024
	global_load_dword v87, v2, s[98:99]
	s_add_u32 s98, s98, 0x10000
	s_addc_u32 s99, s99, 0
	global_load_dwordx2 v[210:211], v4, s[100:101] offset:1536
	global_load_dword v88, v2, s[98:99]
	s_add_u32 s98, s98, 0x10000
	s_addc_u32 s99, s99, 0
	global_load_dwordx2 v[212:213], v4, s[100:101] offset:2048
	global_load_dword v89, v2, s[98:99]
	s_add_u32 s98, s98, 0x10000
	s_addc_u32 s99, s99, 0
	global_load_dwordx2 v[214:215], v4, s[100:101] offset:2560
	global_load_dword v90, v2, s[98:99]
	s_add_u32 s98, s98, 0x10000
	s_addc_u32 s99, s99, 0
	global_load_dwordx2 v[216:217], v4, s[100:101] offset:3072
	global_load_dword v91, v2, s[98:99]
	s_add_u32 s98, s98, 0x10000
	s_addc_u32 s99, s99, 0
	global_load_dwordx2 v[218:219], v4, s[100:101] offset:3584
	s_add_u32 s100, s100, 0x1000
	s_addc_u32 s101, s101, 0
	s_add_u32 s98, s34, 0x5a00000
	s_addc_u32 s99, s35, 0
	s_waitcnt vmcnt(63)
	v_cvt_pk_bf16_f32 v16, v6, v7
	v_lshlrev_b32_e32 v10, 16, v28
	v_and_b32_e32 v11, 0xffff0000, v28
	global_store_dword v2, v16, s[98:99]
	v_pk_fma_f32 v[6:7], v[6:7], v[92:93], v[10:11]
	s_add_u32 s98, s98, 0x10000
	s_addc_u32 s99, s99, 0
	s_waitcnt vmcnt(63)
	v_cvt_pk_bf16_f32 v17, v6, v7
	v_lshlrev_b32_e32 v10, 16, v29
	v_and_b32_e32 v11, 0xffff0000, v29
	global_store_dword v2, v17, s[98:99]
	v_pk_fma_f32 v[6:7], v[6:7], v[94:95], v[10:11]
	s_add_u32 s98, s98, 0x10000
	s_addc_u32 s99, s99, 0
	s_waitcnt vmcnt(63)
	v_cvt_pk_bf16_f32 v18, v6, v7
	v_lshlrev_b32_e32 v10, 16, v30
	v_and_b32_e32 v11, 0xffff0000, v30
	global_store_dword v2, v18, s[98:99]
	v_pk_fma_f32 v[6:7], v[6:7], v[96:97], v[10:11]
	s_add_u32 s98, s98, 0x10000
	s_addc_u32 s99, s99, 0
	s_waitcnt vmcnt(63)
; __device__ __forceinline__ unsigned pk2(float lo, float hi) { f32x2 v = {lo, hi}; bf16x2_t b = __builtin_convertvector(v, bf16x2_t); return __builtin_bit_cast(unsigned, b); }
; __device__ __forceinline__ float bflo(unsigned u) { return __uint_as_float(u << 16); }
; __device__ __forceinline__ float bfhi(unsigned u) { return __uint_as_float(u & 0xffff0000u); }
; __device__ __forceinline__ void gla_scan(Frame& F) {
;     const int NT = F.G * 512;
;     for (int e = F.vcu * 512 + F.tid; e < 8 * 256 * 64; e += NT) {
;         const int bh = e >> 14, rem = e & 16383, dv = rem >> 6, dk = (rem & 63) * 2;
;         unsigned* sb = (unsigned*)(WSP(bf16, WS_SB) + (size_t)bh * 64 * 256 * 128 + (size_t)dv * 128 + dk);
;         const float* dec = WSP(float, WS_DEC) + (size_t)bh * 64 * 128 + dk;
;         float s0 = 0.f, s1 = 0.f;
; #pragma unroll 8
;         for (int n = 0; n < 64; ++n) { const unsigned inc = sb[(size_t)n * 256 * 64]; const f32x2 d = *(const f32x2*)(dec + n * 128);
;             sb[(size_t)n * 256 * 64] = pk2(s0, s1); s0 = d.x * s0 + bflo(inc); s1 = d.y * s1 + bfhi(inc); }
;     }
; }
	v_cvt_pk_bf16_f32 v19, v6, v7
	v_lshlrev_b32_e32 v10, 16, v31
	v_and_b32_e32 v11, 0xffff0000, v31
	global_store_dword v2, v19, s[98:99]
	v_pk_fma_f32 v[6:7], v[6:7], v[98:99], v[10:11]
	s_add_u32 s98, s98, 0x10000
	s_addc_u32 s99, s99, 0
	s_waitcnt vmcnt(63)
	v_cvt_pk_bf16_f32 v16, v6, v7
	v_lshlrev_b32_e32 v10, 16, v32
	v_and_b32_e32 v11, 0xffff0000, v32
	global_store_dword v2, v16, s[98:99]
	v_pk_fma_f32 v[6:7], v[6:7], v[100:101], v[10:11]
	s_add_u32 s98, s98, 0x10000
	s_addc_u32 s99, s99, 0
	s_waitcnt vmcnt(63)
	v_cvt_pk_bf16_f32 v17, v6, v7
	v_lshlrev_b32_e32 v10, 16, v33
	v_and_b32_e32 v11, 0xffff0000, v33
	global_store_dword v2, v17, s[98:99]
	v_pk_fma_f32 v[6:7], v[6:7], v[102:103], v[10:11]
	s_add_u32 s98, s98, 0x10000
	s_addc_u32 s99, s99, 0
	s_waitcnt vmcnt(63)
	v_cvt_pk_bf16_f32 v18, v6, v7
	v_lshlrev_b32_e32 v10, 16, v34
	v_and_b32_e32 v11, 0xffff0000, v34
	global_store_dword v2, v18, s[98:99]
	v_pk_fma_f32 v[6:7], v[6:7], v[104:105], v[10:11]
	s_add_u32 s98, s98, 0x10000
	s_addc_u32 s99, s99, 0
	s_waitcnt vmcnt(63)
	v_cvt_pk_bf16_f32 v19, v6, v7
	v_lshlrev_b32_e32 v10, 16, v35
	v_and_b32_e32 v11, 0xffff0000, v35
	global_store_dword v2, v19, s[98:99]
	v_pk_fma_f32 v[6:7], v[6:7], v[106:107], v[10:11]
	s_add_u32 s98, s98, 0x10000
	s_addc_u32 s99, s99, 0
	s_waitcnt vmcnt(63)
	v_cvt_pk_bf16_f32 v16, v6, v7
	v_lshlrev_b32_e32 v10, 16, v36
	v_and_b32_e32 v11, 0xffff0000, v36
	global_store_dword v2, v16, s[98:99]
	v_pk_fma_f32 v[6:7], v[6:7], v[108:109], v[10:11]
	s_add_u32 s98, s98, 0x10000
	s_addc_u32 s99, s99, 0
	s_waitcnt vmcnt(63)
	v_cvt_pk_bf16_f32 v17, v6, v7
	v_lshlrev_b32_e32 v10, 16, v37
	v_and_b32_e32 v11, 0xffff0000, v37
	global_store_dword v2, v17, s[98:99]
	v_pk_fma_f32 v[6:7], v[6:7], v[110:111], v[10:11]
	s_add_u32 s98, s98, 0x10000
	s_addc_u32 s99, s99, 0
	s_waitcnt vmcnt(63)
	v_cvt_pk_bf16_f32 v18, v6, v7
	v_lshlrev_b32_e32 v10, 16, v38
	v_and_b32_e32 v11, 0xffff0000, v38
	global_store_dword v2, v18, s[98:99]
	v_pk_fma_f32 v[6:7], v[6:7], v[112:113], v[10:11]
	s_add_u32 s98, s98, 0x10000
	s_addc_u32 s99, s99, 0
	s_waitcnt vmcnt(63)
	v_cvt_pk_bf16_f32 v19, v6, v7
	v_lshlrev_b32_e32 v10, 16, v39
	v_and_b32_e32 v11, 0xffff0000, v39
	global_store_dword v2, v19, s[98:99]
	v_pk_fma_f32 v[6:7], v[6:7], v[114:115], v[10:11]
	s_add_u32 s98, s98, 0x10000
	s_addc_u32 s99, s99, 0
	s_waitcnt vmcnt(63)
	v_cvt_pk_bf16_f32 v16, v6, v7
	v_lshlrev_b32_e32 v10, 16, v40
	v_and_b32_e32 v11, 0xffff0000, v40
	global_store_dword v2, v16, s[98:99]
	v_pk_fma_f32 v[6:7], v[6:7], v[116:117], v[10:11]
	s_add_u32 s98, s98, 0x10000
	s_addc_u32 s99, s99, 0
	s_waitcnt vmcnt(63)
	v_cvt_pk_bf16_f32 v17, v6, v7
	v_lshlrev_b32_e32 v10, 16, v41
	v_and_b32_e32 v11, 0xffff0000, v41
	global_store_dword v2, v17, s[98:99]
	v_pk_fma_f32 v[6:7], v[6:7], v[118:119], v[10:11]
	s_add_u32 s98, s98, 0x10000
	s_addc_u32 s99, s99, 0
	s_waitcnt vmcnt(63)
	v_cvt_pk_bf16_f32 v18, v6, v7
	v_lshlrev_b32_e32 v10, 16, v42
	v_and_b32_e32 v11, 0xffff0000, v42
	global_store_dword v2, v18, s[98:99]
	v_pk_fma_f32 v[6:7], v[6:7], v[120:121], v[10:11]
	s_add_u32 s98, s98, 0x10000
	s_addc_u32 s99, s99, 0
	s_waitcnt vmcnt(63)
	v_cvt_pk_bf16_f32 v19, v6, v7
	v_lshlrev_b32_e32 v10, 16, v43
	v_and_b32_e32 v11, 0xffff0000, v43
	global_store_dword v2, v19, s[98:99]
	v_pk_fma_f32 v[6:7], v[6:7], v[122:123], v[10:11]
	s_add_u32 s98, s98, 0x10000
	s_addc_u32 s99, s99, 0
	s_waitcnt vmcnt(63)
	v_cvt_pk_bf16_f32 v16, v6, v7
	v_lshlrev_b32_e32 v10, 16, v44
	v_and_b32_e32 v11, 0xffff0000, v44
	global_store_dword v2, v16, s[98:99]
	v_pk_fma_f32 v[6:7], v[6:7], v[124:125], v[10:11]
	s_add_u32 s98, s98, 0x10000
	s_addc_u32 s99, s99, 0
	s_waitcnt vmcnt(63)
	v_cvt_pk_bf16_f32 v17, v6, v7
	v_lshlrev_b32_e32 v10, 16, v45
	v_and_b32_e32 v11, 0xffff0000, v45
	global_store_dword v2, v17, s[98:99]
	v_pk_fma_f32 v[6:7], v[6:7], v[126:127], v[10:11]
	s_add_u32 s98, s98, 0x10000
	s_addc_u32 s99, s99, 0
	s_waitcnt vmcnt(63)
	v_cvt_pk_bf16_f32 v18, v6, v7
	v_lshlrev_b32_e32 v10, 16, v46
	v_and_b32_e32 v11, 0xffff0000, v46
	global_store_dword v2, v18, s[98:99]
	v_pk_fma_f32 v[6:7], v[6:7], v[128:129], v[10:11]
	s_add_u32 s98, s98, 0x10000
	s_addc_u32 s99, s99, 0
	s_waitcnt vmcnt(63)
	v_cvt_pk_bf16_f32 v19, v6, v7
	v_lshlrev_b32_e32 v10, 16, v47
	v_and_b32_e32 v11, 0xffff0000, v47
	global_store_dword v2, v19, s[98:99]
	v_pk_fma_f32 v[6:7], v[6:7], v[130:131], v[10:11]
	s_add_u32 s98, s98, 0x10000
	s_addc_u32 s99, s99, 0
	s_waitcnt vmcnt(63)
	v_cvt_pk_bf16_f32 v16, v6, v7
	v_lshlrev_b32_e32 v10, 16, v48
	v_and_b32_e32 v11, 0xffff0000, v48
	global_store_dword v2, v16, s[98:99]
	v_pk_fma_f32 v[6:7], v[6:7], v[132:133], v[10:11]
	s_add_u32 s98, s98, 0x10000
	s_addc_u32 s99, s99, 0
	s_waitcnt vmcnt(63)
	v_cvt_pk_bf16_f32 v17, v6, v7
	v_lshlrev_b32_e32 v10, 16, v49
	v_and_b32_e32 v11, 0xffff0000, v49
	global_store_dword v2, v17, s[98:99]
	v_pk_fma_f32 v[6:7], v[6:7], v[134:135], v[10:11]
	s_add_u32 s98, s98, 0x10000
	s_addc_u32 s99, s99, 0
	s_waitcnt vmcnt(63)
	v_cvt_pk_bf16_f32 v18, v6, v7
	v_lshlrev_b32_e32 v10, 16, v50
	v_and_b32_e32 v11, 0xffff0000, v50
	global_store_dword v2, v18, s[98:99]
	v_pk_fma_f32 v[6:7], v[6:7], v[136:137], v[10:11]
	s_add_u32 s98, s98, 0x10000
	s_addc_u32 s99, s99, 0
	s_waitcnt vmcnt(63)
	v_cvt_pk_bf16_f32 v19, v6, v7
	v_lshlrev_b32_e32 v10, 16, v51
	v_and_b32_e32 v11, 0xffff0000, v51
	global_store_dword v2, v19, s[98:99]
	v_pk_fma_f32 v[6:7], v[6:7], v[138:139], v[10:11]
	s_add_u32 s98, s98, 0x10000
	s_addc_u32 s99, s99, 0
	s_waitcnt vmcnt(63)
	v_cvt_pk_bf16_f32 v16, v6, v7
	v_lshlrev_b32_e32 v10, 16, v52
	v_and_b32_e32 v11, 0xffff0000, v52
	global_store_dword v2, v16, s[98:99]
	v_pk_fma_f32 v[6:7], v[6:7], v[140:141], v[10:11]
	s_add_u32 s98, s98, 0x10000
	s_addc_u32 s99, s99, 0
	s_waitcnt vmcnt(63)
; __device__ __forceinline__ unsigned pk2(float lo, float hi) { f32x2 v = {lo, hi}; bf16x2_t b = __builtin_convertvector(v, bf16x2_t); return __builtin_bit_cast(unsigned, b); }
; __device__ __forceinline__ float bflo(unsigned u) { return __uint_as_float(u << 16); }
; __device__ __forceinline__ float bfhi(unsigned u) { return __uint_as_float(u & 0xffff0000u); }
; __device__ __forceinline__ void gla_scan(Frame& F) {
;     const int NT = F.G * 512;
;     for (int e = F.vcu * 512 + F.tid; e < 8 * 256 * 64; e += NT) {
;         const int bh = e >> 14, rem = e & 16383, dv = rem >> 6, dk = (rem & 63) * 2;
;         unsigned* sb = (unsigned*)(WSP(bf16, WS_SB) + (size_t)bh * 64 * 256 * 128 + (size_t)dv * 128 + dk);
;         const float* dec = WSP(float, WS_DEC) + (size_t)bh * 64 * 128 + dk;
;         float s0 = 0.f, s1 = 0.f;
; #pragma unroll 8
;         for (int n = 0; n < 64; ++n) { const unsigned inc = sb[(size_t)n * 256 * 64]; const f32x2 d = *(const f32x2*)(dec + n * 128);
;             sb[(size_t)n * 256 * 64] = pk2(s0, s1); s0 = d.x * s0 + bflo(inc); s1 = d.y * s1 + bfhi(inc); }
;     }
; }
	v_cvt_pk_bf16_f32 v17, v6, v7
	v_lshlrev_b32_e32 v10, 16, v53
	v_and_b32_e32 v11, 0xffff0000, v53
	global_store_dword v2, v17, s[98:99]
	v_pk_fma_f32 v[6:7], v[6:7], v[142:143], v[10:11]
	s_add_u32 s98, s98, 0x10000
	s_addc_u32 s99, s99, 0
	s_waitcnt vmcnt(63)
	v_cvt_pk_bf16_f32 v18, v6, v7
	v_lshlrev_b32_e32 v10, 16, v54
	v_and_b32_e32 v11, 0xffff0000, v54
	global_store_dword v2, v18, s[98:99]
	v_pk_fma_f32 v[6:7], v[6:7], v[144:145], v[10:11]
	s_add_u32 s98, s98, 0x10000
	s_addc_u32 s99, s99, 0
	s_waitcnt vmcnt(63)
	v_cvt_pk_bf16_f32 v19, v6, v7
	v_lshlrev_b32_e32 v10, 16, v55
	v_and_b32_e32 v11, 0xffff0000, v55
	global_store_dword v2, v19, s[98:99]
	v_pk_fma_f32 v[6:7], v[6:7], v[146:147], v[10:11]
	s_add_u32 s98, s98, 0x10000
	s_addc_u32 s99, s99, 0
	s_waitcnt vmcnt(63)
	v_cvt_pk_bf16_f32 v16, v6, v7
	v_lshlrev_b32_e32 v10, 16, v56
	v_and_b32_e32 v11, 0xffff0000, v56
	global_store_dword v2, v16, s[98:99]
	v_pk_fma_f32 v[6:7], v[6:7], v[148:149], v[10:11]
	s_add_u32 s98, s98, 0x10000
	s_addc_u32 s99, s99, 0
	s_waitcnt vmcnt(63)
	v_cvt_pk_bf16_f32 v17, v6, v7
	v_lshlrev_b32_e32 v10, 16, v57
	v_and_b32_e32 v11, 0xffff0000, v57
	global_store_dword v2, v17, s[98:99]
	v_pk_fma_f32 v[6:7], v[6:7], v[150:151], v[10:11]
	s_add_u32 s98, s98, 0x10000
	s_addc_u32 s99, s99, 0
	s_waitcnt vmcnt(63)
	v_cvt_pk_bf16_f32 v18, v6, v7
	v_lshlrev_b32_e32 v10, 16, v58
	v_and_b32_e32 v11, 0xffff0000, v58
	global_store_dword v2, v18, s[98:99]
	v_pk_fma_f32 v[6:7], v[6:7], v[152:153], v[10:11]
	s_add_u32 s98, s98, 0x10000
	s_addc_u32 s99, s99, 0
	s_waitcnt vmcnt(63)
	v_cvt_pk_bf16_f32 v19, v6, v7
	v_lshlrev_b32_e32 v10, 16, v59
	v_and_b32_e32 v11, 0xffff0000, v59
	global_store_dword v2, v19, s[98:99]
	v_pk_fma_f32 v[6:7], v[6:7], v[154:155], v[10:11]
	s_add_u32 s98, s98, 0x10000
	s_addc_u32 s99, s99, 0
	s_waitcnt vmcnt(63)
	v_cvt_pk_bf16_f32 v16, v6, v7
	v_lshlrev_b32_e32 v10, 16, v60
	v_and_b32_e32 v11, 0xffff0000, v60
	global_store_dword v2, v16, s[98:99]
	v_pk_fma_f32 v[6:7], v[6:7], v[156:157], v[10:11]
	s_add_u32 s98, s98, 0x10000
	s_addc_u32 s99, s99, 0
	s_waitcnt vmcnt(63)
	v_cvt_pk_bf16_f32 v17, v6, v7
	v_lshlrev_b32_e32 v10, 16, v61
	v_and_b32_e32 v11, 0xffff0000, v61
	global_store_dword v2, v17, s[98:99]
	v_pk_fma_f32 v[6:7], v[6:7], v[158:159], v[10:11]
	s_add_u32 s98, s98, 0x10000
	s_addc_u32 s99, s99, 0
	s_waitcnt vmcnt(63)
	v_cvt_pk_bf16_f32 v18, v6, v7
	v_lshlrev_b32_e32 v10, 16, v62
	v_and_b32_e32 v11, 0xffff0000, v62
	global_store_dword v2, v18, s[98:99]
	v_pk_fma_f32 v[6:7], v[6:7], v[160:161], v[10:11]
	s_add_u32 s98, s98, 0x10000
	s_addc_u32 s99, s99, 0
	s_waitcnt vmcnt(63)
	v_cvt_pk_bf16_f32 v19, v6, v7
	v_lshlrev_b32_e32 v10, 16, v63
	v_and_b32_e32 v11, 0xffff0000, v63
	global_store_dword v2, v19, s[98:99]
	v_pk_fma_f32 v[6:7], v[6:7], v[162:163], v[10:11]
	s_add_u32 s98, s98, 0x10000
	s_addc_u32 s99, s99, 0
	s_waitcnt vmcnt(63)
	v_cvt_pk_bf16_f32 v16, v6, v7
	v_lshlrev_b32_e32 v10, 16, v64
	v_and_b32_e32 v11, 0xffff0000, v64
	global_store_dword v2, v16, s[98:99]
	v_pk_fma_f32 v[6:7], v[6:7], v[164:165], v[10:11]
	s_add_u32 s98, s98, 0x10000
	s_addc_u32 s99, s99, 0
	s_waitcnt vmcnt(63)
	v_cvt_pk_bf16_f32 v17, v6, v7
	v_lshlrev_b32_e32 v10, 16, v65
	v_and_b32_e32 v11, 0xffff0000, v65
	global_store_dword v2, v17, s[98:99]
	v_pk_fma_f32 v[6:7], v[6:7], v[166:167], v[10:11]
	s_add_u32 s98, s98, 0x10000
	s_addc_u32 s99, s99, 0
	s_waitcnt vmcnt(63)
	v_cvt_pk_bf16_f32 v18, v6, v7
	v_lshlrev_b32_e32 v10, 16, v66
	v_and_b32_e32 v11, 0xffff0000, v66
	global_store_dword v2, v18, s[98:99]
	v_pk_fma_f32 v[6:7], v[6:7], v[168:169], v[10:11]
	s_add_u32 s98, s98, 0x10000
	s_addc_u32 s99, s99, 0
	s_waitcnt vmcnt(63)
	v_cvt_pk_bf16_f32 v19, v6, v7
	v_lshlrev_b32_e32 v10, 16, v67
	v_and_b32_e32 v11, 0xffff0000, v67
	global_store_dword v2, v19, s[98:99]
	v_pk_fma_f32 v[6:7], v[6:7], v[170:171], v[10:11]
	s_add_u32 s98, s98, 0x10000
	s_addc_u32 s99, s99, 0
	s_waitcnt vmcnt(63)
	v_cvt_pk_bf16_f32 v16, v6, v7
	v_lshlrev_b32_e32 v10, 16, v68
	v_and_b32_e32 v11, 0xffff0000, v68
	global_store_dword v2, v16, s[98:99]
	v_pk_fma_f32 v[6:7], v[6:7], v[172:173], v[10:11]
	s_add_u32 s98, s98, 0x10000
	s_addc_u32 s99, s99, 0
	s_waitcnt vmcnt(63)
	v_cvt_pk_bf16_f32 v17, v6, v7
	v_lshlrev_b32_e32 v10, 16, v69
	v_and_b32_e32 v11, 0xffff0000, v69
	global_store_dword v2, v17, s[98:99]
	v_pk_fma_f32 v[6:7], v[6:7], v[174:175], v[10:11]
	s_add_u32 s98, s98, 0x10000
	s_addc_u32 s99, s99, 0
	s_waitcnt vmcnt(63)
	v_cvt_pk_bf16_f32 v18, v6, v7
	v_lshlrev_b32_e32 v10, 16, v70
	v_and_b32_e32 v11, 0xffff0000, v70
	global_store_dword v2, v18, s[98:99]
	v_pk_fma_f32 v[6:7], v[6:7], v[176:177], v[10:11]
	s_add_u32 s98, s98, 0x10000
	s_addc_u32 s99, s99, 0
	s_waitcnt vmcnt(63)
	v_cvt_pk_bf16_f32 v19, v6, v7
	v_lshlrev_b32_e32 v10, 16, v71
	v_and_b32_e32 v11, 0xffff0000, v71
	global_store_dword v2, v19, s[98:99]
	v_pk_fma_f32 v[6:7], v[6:7], v[178:179], v[10:11]
	s_add_u32 s98, s98, 0x10000
	s_addc_u32 s99, s99, 0
	s_waitcnt vmcnt(63)
	v_cvt_pk_bf16_f32 v16, v6, v7
	v_lshlrev_b32_e32 v10, 16, v72
	v_and_b32_e32 v11, 0xffff0000, v72
	global_store_dword v2, v16, s[98:99]
	v_pk_fma_f32 v[6:7], v[6:7], v[180:181], v[10:11]
	s_add_u32 s98, s98, 0x10000
	s_addc_u32 s99, s99, 0
	s_waitcnt vmcnt(63)
; __device__ __forceinline__ unsigned pk2(float lo, float hi) { f32x2 v = {lo, hi}; bf16x2_t b = __builtin_convertvector(v, bf16x2_t); return __builtin_bit_cast(unsigned, b); }
; __device__ __forceinline__ float bflo(unsigned u) { return __uint_as_float(u << 16); }
; __device__ __forceinline__ float bfhi(unsigned u) { return __uint_as_float(u & 0xffff0000u); }
; __device__ __forceinline__ void gla_scan(Frame& F) {
;     const int NT = F.G * 512;
;     for (int e = F.vcu * 512 + F.tid; e < 8 * 256 * 64; e += NT) {
;         const int bh = e >> 14, rem = e & 16383, dv = rem >> 6, dk = (rem & 63) * 2;
;         unsigned* sb = (unsigned*)(WSP(bf16, WS_SB) + (size_t)bh * 64 * 256 * 128 + (size_t)dv * 128 + dk);
;         const float* dec = WSP(float, WS_DEC) + (size_t)bh * 64 * 128 + dk;
;         float s0 = 0.f, s1 = 0.f;
; #pragma unroll 8
;         for (int n = 0; n < 64; ++n) { const unsigned inc = sb[(size_t)n * 256 * 64]; const f32x2 d = *(const f32x2*)(dec + n * 128);
;             sb[(size_t)n * 256 * 64] = pk2(s0, s1); s0 = d.x * s0 + bflo(inc); s1 = d.y * s1 + bfhi(inc); }
;     }
; }
	v_cvt_pk_bf16_f32 v17, v6, v7
	v_lshlrev_b32_e32 v10, 16, v73
	v_and_b32_e32 v11, 0xffff0000, v73
	global_store_dword v2, v17, s[98:99]
	v_pk_fma_f32 v[6:7], v[6:7], v[182:183], v[10:11]
	s_add_u32 s98, s98, 0x10000
	s_addc_u32 s99, s99, 0
	s_waitcnt vmcnt(63)
	v_cvt_pk_bf16_f32 v18, v6, v7
	v_lshlrev_b32_e32 v10, 16, v74
	v_and_b32_e32 v11, 0xffff0000, v74
	global_store_dword v2, v18, s[98:99]
	v_pk_fma_f32 v[6:7], v[6:7], v[184:185], v[10:11]
	s_add_u32 s98, s98, 0x10000
	s_addc_u32 s99, s99, 0
	s_waitcnt vmcnt(63)
	v_cvt_pk_bf16_f32 v19, v6, v7
	v_lshlrev_b32_e32 v10, 16, v75
	v_and_b32_e32 v11, 0xffff0000, v75
	global_store_dword v2, v19, s[98:99]
	v_pk_fma_f32 v[6:7], v[6:7], v[186:187], v[10:11]
	s_add_u32 s98, s98, 0x10000
	s_addc_u32 s99, s99, 0
	s_waitcnt vmcnt(63)
	v_cvt_pk_bf16_f32 v16, v6, v7
	v_lshlrev_b32_e32 v10, 16, v76
	v_and_b32_e32 v11, 0xffff0000, v76
	global_store_dword v2, v16, s[98:99]
	v_pk_fma_f32 v[6:7], v[6:7], v[188:189], v[10:11]
	s_add_u32 s98, s98, 0x10000
	s_addc_u32 s99, s99, 0
	s_waitcnt vmcnt(63)
	v_cvt_pk_bf16_f32 v17, v6, v7
	v_lshlrev_b32_e32 v10, 16, v77
	v_and_b32_e32 v11, 0xffff0000, v77
	global_store_dword v2, v17, s[98:99]
	v_pk_fma_f32 v[6:7], v[6:7], v[190:191], v[10:11]
	s_add_u32 s98, s98, 0x10000
	s_addc_u32 s99, s99, 0
	s_waitcnt vmcnt(63)
	v_cvt_pk_bf16_f32 v18, v6, v7
	v_lshlrev_b32_e32 v10, 16, v78
	v_and_b32_e32 v11, 0xffff0000, v78
	global_store_dword v2, v18, s[98:99]
	v_pk_fma_f32 v[6:7], v[6:7], v[192:193], v[10:11]
	s_add_u32 s98, s98, 0x10000
	s_addc_u32 s99, s99, 0
	s_waitcnt vmcnt(63)
	v_cvt_pk_bf16_f32 v19, v6, v7
	v_lshlrev_b32_e32 v10, 16, v79
	v_and_b32_e32 v11, 0xffff0000, v79
	global_store_dword v2, v19, s[98:99]
	v_pk_fma_f32 v[6:7], v[6:7], v[194:195], v[10:11]
	s_add_u32 s98, s98, 0x10000
	s_addc_u32 s99, s99, 0
	s_waitcnt vmcnt(63)
	v_cvt_pk_bf16_f32 v16, v6, v7
	v_lshlrev_b32_e32 v10, 16, v80
	v_and_b32_e32 v11, 0xffff0000, v80
	global_store_dword v2, v16, s[98:99]
	v_pk_fma_f32 v[6:7], v[6:7], v[196:197], v[10:11]
	s_add_u32 s98, s98, 0x10000
	s_addc_u32 s99, s99, 0
	s_waitcnt vmcnt(63)
	v_cvt_pk_bf16_f32 v17, v6, v7
	v_lshlrev_b32_e32 v10, 16, v81
	v_and_b32_e32 v11, 0xffff0000, v81
	global_store_dword v2, v17, s[98:99]
	v_pk_fma_f32 v[6:7], v[6:7], v[198:199], v[10:11]
	s_add_u32 s98, s98, 0x10000
	s_addc_u32 s99, s99, 0
	s_waitcnt vmcnt(63)
	v_cvt_pk_bf16_f32 v18, v6, v7
	v_lshlrev_b32_e32 v10, 16, v82
	v_and_b32_e32 v11, 0xffff0000, v82
	global_store_dword v2, v18, s[98:99]
	v_pk_fma_f32 v[6:7], v[6:7], v[200:201], v[10:11]
	s_add_u32 s98, s98, 0x10000
	s_addc_u32 s99, s99, 0
	s_waitcnt vmcnt(63)
	v_cvt_pk_bf16_f32 v19, v6, v7
	v_lshlrev_b32_e32 v10, 16, v83
	v_and_b32_e32 v11, 0xffff0000, v83
	global_store_dword v2, v19, s[98:99]
	v_pk_fma_f32 v[6:7], v[6:7], v[202:203], v[10:11]
	s_add_u32 s98, s98, 0x10000
	s_addc_u32 s99, s99, 0
	s_waitcnt vmcnt(63)
	v_cvt_pk_bf16_f32 v16, v6, v7
	v_lshlrev_b32_e32 v10, 16, v84
	v_and_b32_e32 v11, 0xffff0000, v84
	global_store_dword v2, v16, s[98:99]
	v_pk_fma_f32 v[6:7], v[6:7], v[204:205], v[10:11]
	s_add_u32 s98, s98, 0x10000
	s_addc_u32 s99, s99, 0
	s_waitcnt vmcnt(63)
	v_cvt_pk_bf16_f32 v17, v6, v7
	v_lshlrev_b32_e32 v10, 16, v85
	v_and_b32_e32 v11, 0xffff0000, v85
	global_store_dword v2, v17, s[98:99]
	v_pk_fma_f32 v[6:7], v[6:7], v[206:207], v[10:11]
	s_add_u32 s98, s98, 0x10000
	s_addc_u32 s99, s99, 0
	s_waitcnt vmcnt(63)
	v_cvt_pk_bf16_f32 v18, v6, v7
	v_lshlrev_b32_e32 v10, 16, v86
	v_and_b32_e32 v11, 0xffff0000, v86
	global_store_dword v2, v18, s[98:99]
	v_pk_fma_f32 v[6:7], v[6:7], v[208:209], v[10:11]
	s_add_u32 s98, s98, 0x10000
	s_addc_u32 s99, s99, 0
	s_waitcnt vmcnt(63)
	v_cvt_pk_bf16_f32 v19, v6, v7
	v_lshlrev_b32_e32 v10, 16, v87
	v_and_b32_e32 v11, 0xffff0000, v87
	global_store_dword v2, v19, s[98:99]
	v_pk_fma_f32 v[6:7], v[6:7], v[210:211], v[10:11]
	s_add_u32 s98, s98, 0x10000
	s_addc_u32 s99, s99, 0
	s_waitcnt vmcnt(63)
	v_cvt_pk_bf16_f32 v16, v6, v7
	v_lshlrev_b32_e32 v10, 16, v88
	v_and_b32_e32 v11, 0xffff0000, v88
	global_store_dword v2, v16, s[98:99]
	v_pk_fma_f32 v[6:7], v[6:7], v[212:213], v[10:11]
	s_add_u32 s98, s98, 0x10000
	s_addc_u32 s99, s99, 0
	s_waitcnt vmcnt(63)
	v_cvt_pk_bf16_f32 v17, v6, v7
	v_lshlrev_b32_e32 v10, 16, v89
	v_and_b32_e32 v11, 0xffff0000, v89
	global_store_dword v2, v17, s[98:99]
	v_pk_fma_f32 v[6:7], v[6:7], v[214:215], v[10:11]
	s_add_u32 s98, s98, 0x10000
	s_addc_u32 s99, s99, 0
	s_waitcnt vmcnt(63)
	v_cvt_pk_bf16_f32 v18, v6, v7
	v_lshlrev_b32_e32 v10, 16, v90
	v_and_b32_e32 v11, 0xffff0000, v90
	global_store_dword v2, v18, s[98:99]
	v_pk_fma_f32 v[6:7], v[6:7], v[216:217], v[10:11]
	s_add_u32 s98, s98, 0x10000
	s_addc_u32 s99, s99, 0
	s_waitcnt vmcnt(63)
	v_cvt_pk_bf16_f32 v19, v6, v7
	v_lshlrev_b32_e32 v10, 16, v91
	v_and_b32_e32 v11, 0xffff0000, v91
	global_store_dword v2, v19, s[98:99]
	v_pk_fma_f32 v[6:7], v[6:7], v[218:219], v[10:11]
	s_add_u32 s98, s98, 0x10000
	s_addc_u32 s99, s99, 0
	v_add_u32_e32 v8, s3, v8
	v_cmp_lt_i32_e32 vcc, s15, v8
	s_or_b64 s[8:9], vcc, s[8:9]
	v_add_u32_e32 v9, s12, v9
	s_andn2_b64 exec, exec, s[8:9]
	s_cbranch_execnz .LBB0_696
